# attention key loop software-pipelined across K/V tiles (both LDS buffers resident, one mid-tile barrier per tile) on top of matrix-core row sums
# speedup vs baseline: 1.0248x; 1.0022x over previous
.LBB0_765:
	s_mul_i32 s0, s36, 0x1dc0000
	s_mul_hi_i32 s1, s36, 0x1dc0000
	s_add_u32 s0, s24, s0
	s_addc_u32 s1, s25, s1
	s_lshl_b32 s6, s4, 6
	s_and_b32 s33, s6, 0xc0
	s_lshl_b32 s22, s33, 1
	s_cmp_lt_u32 s5, 2
	v_mov_b32_e32 v18, v222
	s_cselect_b32 s38, 4, 0x44
	v_lshlrev_b32_e32 v0, 4, v18
	s_add_u32 s6, s0, s22
	v_and_b32_e32 v4, 0x70, v0
	v_mov_b32_e32 v5, v3
	s_addc_u32 s7, s1, 0
	v_lshl_add_u64 v[0:1], s[6:7], 0, v[4:5]
	s_mov_b64 s[6:7], 0x1600
	v_ashrrev_i32_e32 v19, 3, v18
	v_lshl_add_u64 v[6:7], v[0:1], 0, s[6:7]
	s_mov_b64 s[6:7], 0x1800
	v_lshl_add_u64 v[0:1], v[0:1], 0, s[6:7]
	v_add_u32_e32 v2, 32, v19
	v_mad_i64_i32 v[10:11], s[6:7], v19, s48, v[0:1]
	v_mad_i64_i32 v[12:13], s[6:7], v2, s48, v[0:1]
	v_ashrrev_i32_e32 v0, 1, v18
	v_and_b32_e32 v0, 0xffffffe0, v0
	v_and_b32_e32 v5, 31, v18
	v_lshl_add_u32 v0, s5, 7, v0
	v_or_b32_e32 v148, v0, v5
	v_mov_b64_e32 v[0:1], s[0:1]
	v_bfe_u32 v219, v18, 5, 1
	v_mad_i64_i32 v[0:1], s[0:1], v148, s48, v[0:1]
	v_mad_i64_i32 v[8:9], s[6:7], v19, s48, v[6:7]
	v_mad_i64_i32 v[6:7], s[6:7], v2, s48, v[6:7]
	v_lshl_add_u64 v[14:15], v[0:1], 0, s[22:23]
	v_lshlrev_b32_e32 v2, 4, v219
	v_lshl_add_u64 v[14:15], v[14:15], 0, v[2:3]
	s_mov_b64 s[0:1], 0x1400
	v_lshl_add_u64 v[16:17], v[14:15], 0, s[0:1]
	s_movk_i32 s0, 0x1000
	v_add_co_u32_e32 v14, vcc, s0, v14
	s_mov_b32 s0, 0x70000
	s_nop 0
	v_addc_co_u32_e32 v15, vcc, 0, v15, vcc
	global_load_dwordx4 v[100:103], v[8:9], off
	global_load_dwordx4 v[104:107], v[6:7], off
	v_add_co_u32_e32 v8, vcc, s0, v8
	global_load_dwordx4 v[112:115], v[10:11], off
	global_load_dwordx4 v[128:131], v[12:13], off
	v_addc_co_u32_e32 v9, vcc, 0, v9, vcc
	v_add_co_u32_e32 v6, vcc, s0, v6
	global_load_dwordx4 v[108:111], v[16:17], off offset:32
	global_load_dwordx4 v[116:119], v[16:17], off offset:64
	global_load_dwordx4 v[120:123], v[14:15], off offset:1024
	global_load_dwordx4 v[124:127], v[16:17], off offset:96
	v_addc_co_u32_e32 v7, vcc, 0, v7, vcc
	global_load_dwordx4 v[132:135], v[8:9], off
	global_load_dwordx4 v[136:139], v[6:7], off
	v_add_co_u32_e32 v6, vcc, s0, v10
	v_mul_u32_u24_e32 v5, 0x48, v5
	s_nop 0
	v_addc_co_u32_e32 v7, vcc, 0, v11, vcc
	v_add_co_u32_e32 v8, vcc, s0, v12
	s_movk_i32 s0, 0x90
	s_nop 0
	v_addc_co_u32_e32 v9, vcc, 0, v13, vcc
	global_load_dwordx4 v[140:143], v[6:7], off
	global_load_dwordx4 v[144:147], v[8:9], off
	v_lshrrev_b32_e32 v6, 3, v18
	v_bfe_u32 v7, v18, 2, 2
	v_mul_lo_u32 v9, v19, s0
	v_and_b32_e32 v8, 16, v18
	v_and_or_b32 v6, v6, 4, v7
	v_add3_u32 v239, 32, v9, v4
	v_lshlrev_b32_e32 v4, 2, v18
	v_lshlrev_b32_e32 v5, 1, v5
	v_and_or_b32 v4, v4, 12, v8
	v_add3_u32 v240, 32, v5, v2
	v_mul_u32_u24_e32 v5, 0x48, v6
	v_lshlrev_b32_e32 v4, 1, v4
	v_lshlrev_b32_e32 v5, 1, v5
	v_add3_u32 v241, 32, v4, v5
	v_add3_u32 v242, 32, v5, v4
	v_mad_i64_i32 v[4:5], s[0:1], v19, s48, 0
	v_mad_i64_i32 v[4:5], s[0:1], s36, v237, v[4:5]
	s_and_b32 s0, s4, 3
	v_and_b32_e32 v6, 7, v18
	s_lshl_b32 s0, s0, 7
	v_lshlrev_b32_e32 v6, 4, v6
	v_or3_b32 v4, v4, s0, v6
	v_mov_b32_e32 v18, v3
	v_mov_b32_e32 v19, v3
	v_lshl_add_u64 v[150:151], s[30:31], 0, v[4:5]
	v_mov_b32_e32 v4, v3
	v_mov_b32_e32 v5, v3
	v_mov_b32_e32 v6, v3
	v_mov_b32_e32 v7, v3
	v_mov_b32_e32 v8, v3
	v_mov_b32_e32 v9, v3
	v_mov_b32_e32 v10, v3
	v_mov_b32_e32 v11, v3
	v_mov_b32_e32 v12, v3
	v_mov_b32_e32 v13, v3
	v_mov_b32_e32 v14, v3
	v_mov_b32_e32 v15, v3
	v_mov_b32_e32 v16, v3
	v_mov_b32_e32 v17, v3
	s_waitcnt vmcnt(22)
	v_mov_b64_e32 v[34:35], v[18:19]
	s_waitcnt vmcnt(20)
	v_mov_b64_e32 v[66:67], v[18:19]
	v_mov_b64_e32 v[50:51], v[18:19]
	s_mov_b32 s39, 0
	v_ashrrev_i32_e32 v149, 31, v148
	v_mov_b32_e32 v153, 0
	s_mov_b64 s[0:1], 0
	v_mov_b64_e32 v[32:33], v[16:17]
	v_mov_b64_e32 v[30:31], v[14:15]
	v_mov_b64_e32 v[28:29], v[12:13]
	v_mov_b64_e32 v[26:27], v[10:11]
	v_mov_b64_e32 v[24:25], v[8:9]
	v_mov_b64_e32 v[22:23], v[6:7]
	v_mov_b64_e32 v[20:21], v[4:5]
	v_mov_b32_e32 v152, 0
	v_mov_b32_e32 v243, 0
	v_mov_b32_e32 v244, 0
	v_mov_b64_e32 v[64:65], v[16:17]
	v_mov_b64_e32 v[62:63], v[14:15]
	v_mov_b64_e32 v[60:61], v[12:13]
	v_mov_b64_e32 v[58:59], v[10:11]
	v_mov_b64_e32 v[56:57], v[8:9]
	v_mov_b64_e32 v[54:55], v[6:7]
	v_mov_b64_e32 v[52:53], v[4:5]
	v_mov_b64_e32 v[48:49], v[16:17]
	v_mov_b64_e32 v[46:47], v[14:15]
	v_mov_b64_e32 v[44:45], v[12:13]
	v_mov_b64_e32 v[42:43], v[10:11]
	v_mov_b64_e32 v[40:41], v[8:9]
	v_mov_b64_e32 v[38:39], v[6:7]
	v_mov_b64_e32 v[36:37], v[4:5]
	s_barrier
	s_waitcnt vmcnt(11)
	ds_write_b128 v239, v[100:103]
	s_waitcnt vmcnt(10)
	ds_write_b128 v239, v[104:107] offset:4608
	s_waitcnt vmcnt(9)
	ds_write_b128 v239, v[112:115] offset:18432
	s_waitcnt vmcnt(8)
	ds_write_b128 v239, v[128:131] offset:23040
	s_waitcnt lgkmcnt(0)
	s_barrier
	v_mov_b32_e32 v223, v219
	v_mov_b32_e32 v254, v239
	s_add_u32 s4, s0, 0x7275000
	s_addc_u32 s5, s1, 0
	s_add_u32 s6, s0, 0x72ad000
	s_addc_u32 s7, s1, 0
	v_lshl_add_u64 v[72:73], v[150:151], 0, s[4:5]
	v_lshl_add_u64 v[74:75], v[150:151], 0, s[6:7]
	global_load_dwordx4 v[100:103], v[72:73], off offset:1536
	global_load_dwordx4 v[112:115], v[72:73], off offset:2048
	global_load_dwordx4 v[104:107], v[74:75], off offset:1536
	global_load_dwordx4 v[128:131], v[74:75], off offset:2048
	v_mov_b32_e32 v224, 0
	v_mov_b32_e32 v225, 0
	v_mov_b32_e32 v226, 0
	v_mov_b32_e32 v227, 0
	v_mov_b32_e32 v228, 0
	v_mov_b32_e32 v229, 0
	v_mov_b32_e32 v230, 0
	v_mov_b32_e32 v231, 0
	v_mov_b32_e32 v232, 0
	v_mov_b32_e32 v233, 0
	v_mov_b32_e32 v234, 0
	v_mov_b32_e32 v235, 0
	v_mov_b32_e32 v236, 0
	v_mov_b32_e32 v237, 0
	v_mov_b32_e32 v238, 0
	v_mov_b32_e32 v239, 0
	v_mov_b32_e32 v244, 0
	v_mov_b32_e32 v245, 0
	v_mov_b32_e32 v246, 0
	v_mov_b32_e32 v247, 0
	v_mov_b32_e32 v248, 0
	v_mov_b32_e32 v249, 0
	v_mov_b32_e32 v250, 0
	v_mov_b32_e32 v251, 0
	v_mov_b32_e32 v243, 0
	v_lshrrev_b32_e32 v218, 4, v222
	v_xor_b32_e32 v218, v218, v222
	v_and_b32_e32 v218, 1, v218
	v_cmp_eq_u32_e32 vcc, 0, v218
	v_mov_b32_e32 v219, 0x3f803f80
	v_cndmask_b32_e32 v218, 0, v219, vcc
	v_mov_b32_e32 v219, v218
	v_mov_b32_e32 v220, v218
	v_mov_b32_e32 v221, v218
	ds_read_b128 v[186:189], v240
	ds_read_b128 v[190:193], v240 offset:32
	ds_read_b128 v[194:197], v240 offset:64
	ds_read_b128 v[198:201], v240 offset:96
	s_waitcnt vmcnt(4)
	ds_write_b128 v254, v[132:135] offset:9216
	ds_write_b128 v254, v[136:139] offset:13824
	ds_write_b128 v254, v[140:143] offset:27648
	ds_write_b128 v254, v[144:147] offset:32256
	s_waitcnt lgkmcnt(0)
	s_barrier
	s_add_u32 s4, s0, 0x72e5000
	s_addc_u32 s5, s1, 0
	s_add_u32 s6, s0, 0x731d000
	s_addc_u32 s7, s1, 0
	v_lshl_add_u64 v[72:73], v[150:151], 0, s[4:5]
	v_lshl_add_u64 v[74:75], v[150:151], 0, s[6:7]
	global_load_dwordx4 v[132:135], v[72:73], off offset:1536
	global_load_dwordx4 v[140:143], v[72:73], off offset:2048
	global_load_dwordx4 v[136:139], v[74:75], off offset:1536
	global_load_dwordx4 v[144:147], v[74:75], off offset:2048
	v_mfma_f32_32x32x16_bf16 v[68:83], v[186:189], v[120:123], v[224:239]
	v_mfma_f32_32x32x16_bf16 v[68:83], v[190:193], v[108:111], v[68:83]
	v_mfma_f32_32x32x16_bf16 v[154:169], v[194:197], v[116:119], v[224:239]
	v_mfma_f32_32x32x16_bf16 v[154:169], v[198:201], v[124:127], v[154:169]
	ds_read_b128 v[202:205], v240 offset:4608
	ds_read_b128 v[206:209], v240 offset:4640
	ds_read_b128 v[210:213], v240 offset:4672
	ds_read_b128 v[214:217], v240 offset:4704
	ds_read_b64_tr_b16 v[186:187], v241 offset:18432
	ds_read_b64_tr_b16 v[188:189], v241 offset:19584
	ds_read_b64_tr_b16 v[190:191], v241 offset:18496
	ds_read_b64_tr_b16 v[192:193], v241 offset:19648
	ds_read_b64_tr_b16 v[194:195], v241 offset:20736
	ds_read_b64_tr_b16 v[196:197], v241 offset:21888
	ds_read_b64_tr_b16 v[198:199], v241 offset:20800
	ds_read_b64_tr_b16 v[200:201], v241 offset:21952
.LBB0_766:
	s_add_i32 s22, s39, 2
	s_cmp_lt_u32 s22, s38
	s_cselect_b64 s[10:11], -1, 0
	s_cmp_ge_u32 s22, s38
	s_cselect_b64 s[12:13], -1, 0
	v_exp_f32_e32 v68, v68
	v_exp_f32_e32 v69, v69
	s_waitcnt lgkmcnt(8)
	v_mfma_f32_32x32x16_bf16 v[84:99], v[202:205], v[120:123], v[224:239]
	ds_read_b64_tr_b16 v[202:203], v242 offset:23040
	ds_read_b64_tr_b16 v[204:205], v242 offset:24192
	v_exp_f32_e32 v70, v70
	v_exp_f32_e32 v71, v71
	v_exp_f32_e32 v72, v72
	v_mfma_f32_32x32x16_bf16 v[84:99], v[206:209], v[108:111], v[84:99]
	ds_read_b64_tr_b16 v[206:207], v242 offset:23104
	ds_read_b64_tr_b16 v[208:209], v242 offset:24256
	v_exp_f32_e32 v73, v73
	v_exp_f32_e32 v74, v74
	v_exp_f32_e32 v75, v75
	v_mfma_f32_32x32x16_bf16 v[170:185], v[210:213], v[116:119], v[224:239]
	ds_read_b64_tr_b16 v[210:211], v242 offset:25344
	ds_read_b64_tr_b16 v[212:213], v242 offset:26496
	v_cvt_pk_bf16_f32 v68, v68, v69
	v_cvt_pk_bf16_f32 v69, v70, v71
	v_cvt_pk_bf16_f32 v70, v72, v73
	v_cvt_pk_bf16_f32 v71, v74, v75
	v_exp_f32_e32 v154, v154
	v_exp_f32_e32 v155, v155
	s_waitcnt lgkmcnt(10)
	v_mfma_f32_32x32x16_bf16 v[4:19], v[186:189], v[68:71], v[4:19]
	v_exp_f32_e32 v156, v156
	v_exp_f32_e32 v157, v157
	v_exp_f32_e32 v158, v158
	v_mfma_f32_32x32x16_bf16 v[20:35], v[190:193], v[68:71], v[20:35]
	v_exp_f32_e32 v159, v159
	v_exp_f32_e32 v160, v160
	v_exp_f32_e32 v161, v161
	v_mfma_f32_16x16x32_bf16 v[244:247], v[68:71], v[218:221], v[244:247]
	v_mfma_f32_32x32x16_bf16 v[170:185], v[214:217], v[124:127], v[170:185]
	ds_read_b64_tr_b16 v[214:215], v242 offset:25408
	ds_read_b64_tr_b16 v[216:217], v242 offset:26560
	v_cvt_pk_bf16_f32 v154, v154, v155
	v_cvt_pk_bf16_f32 v155, v156, v157
	v_cvt_pk_bf16_f32 v156, v158, v159
	v_cvt_pk_bf16_f32 v157, v160, v161
	v_exp_f32_e32 v76, v76
	v_exp_f32_e32 v77, v77
	v_mfma_f32_32x32x16_bf16 v[36:51], v[186:189], v[154:157], v[36:51]
	v_exp_f32_e32 v78, v78
	v_exp_f32_e32 v79, v79
	v_exp_f32_e32 v80, v80
	v_mfma_f32_32x32x16_bf16 v[52:67], v[190:193], v[154:157], v[52:67]
	v_exp_f32_e32 v81, v81
	v_exp_f32_e32 v82, v82
	v_exp_f32_e32 v83, v83
	v_mfma_f32_16x16x32_bf16 v[248:251], v[154:157], v[218:221], v[248:251]
	v_cvt_pk_bf16_f32 v76, v76, v77
	v_cvt_pk_bf16_f32 v77, v78, v79
	v_cvt_pk_bf16_f32 v78, v80, v81
	v_cvt_pk_bf16_f32 v79, v82, v83
	v_exp_f32_e32 v162, v162
	v_exp_f32_e32 v163, v163
	s_waitcnt lgkmcnt(8)
	v_mfma_f32_32x32x16_bf16 v[4:19], v[194:197], v[76:79], v[4:19]
	v_exp_f32_e32 v164, v164
	v_exp_f32_e32 v165, v165
	v_exp_f32_e32 v166, v166
	v_mfma_f32_32x32x16_bf16 v[20:35], v[198:201], v[76:79], v[20:35]
	v_exp_f32_e32 v167, v167
	v_exp_f32_e32 v168, v168
	v_exp_f32_e32 v169, v169
	v_mfma_f32_16x16x32_bf16 v[244:247], v[76:79], v[218:221], v[244:247]
	v_cvt_pk_bf16_f32 v162, v162, v163
	v_cvt_pk_bf16_f32 v163, v164, v165
	v_cvt_pk_bf16_f32 v164, v166, v167
	v_cvt_pk_bf16_f32 v165, v168, v169
	s_waitcnt lgkmcnt(0)
	s_barrier
	s_and_b64 vcc, exec, s[12:13]
	s_cbranch_vccnz .Lat_norefill_a
	s_add_i32 s4, s39, 4
	s_cmp_ge_u32 s4, s38
	s_waitcnt vmcnt(4)
	ds_write_b128 v254, v[100:103]
	ds_write_b128 v254, v[104:107] offset:4608
	ds_write_b128 v254, v[112:115] offset:18432
	ds_write_b128 v254, v[128:131] offset:23040
	s_cbranch_scc1 .Lat_norefill_a
	s_add_u32 s4, s0, 0x7355000
	s_addc_u32 s5, s1, 0
	s_add_u32 s6, s0, 0x738d000
	s_addc_u32 s7, s1, 0
	v_lshl_add_u64 v[72:73], v[150:151], 0, s[4:5]
	v_lshl_add_u64 v[74:75], v[150:151], 0, s[6:7]
	global_load_dwordx4 v[100:103], v[72:73], off offset:1536
	global_load_dwordx4 v[112:115], v[72:73], off offset:2048
	global_load_dwordx4 v[104:107], v[74:75], off offset:1536
	global_load_dwordx4 v[128:131], v[74:75], off offset:2048
.Lat_norefill_a:
	v_exp_f32_e32 v84, v84
	v_exp_f32_e32 v85, v85
	v_mfma_f32_32x32x16_bf16 v[36:51], v[194:197], v[162:165], v[36:51]
	v_exp_f32_e32 v86, v86
	v_exp_f32_e32 v87, v87
	v_exp_f32_e32 v88, v88
	v_mfma_f32_32x32x16_bf16 v[52:67], v[198:201], v[162:165], v[52:67]
	ds_read_b128 v[186:189], v240 offset:9216
	ds_read_b128 v[190:193], v240 offset:9248
	ds_read_b128 v[194:197], v240 offset:9280
	ds_read_b128 v[198:201], v240 offset:9312
	v_exp_f32_e32 v89, v89
	v_exp_f32_e32 v90, v90
	v_exp_f32_e32 v91, v91
	v_mfma_f32_16x16x32_bf16 v[248:251], v[162:165], v[218:221], v[248:251]
	v_cvt_pk_bf16_f32 v84, v84, v85
	v_cvt_pk_bf16_f32 v85, v86, v87
	v_cvt_pk_bf16_f32 v86, v88, v89
	v_cvt_pk_bf16_f32 v87, v90, v91
	v_exp_f32_e32 v170, v170
	v_exp_f32_e32 v171, v171
	v_mfma_f32_32x32x16_bf16 v[4:19], v[202:205], v[84:87], v[4:19]
	v_exp_f32_e32 v172, v172
	v_exp_f32_e32 v173, v173
	v_exp_f32_e32 v174, v174
	v_mfma_f32_32x32x16_bf16 v[20:35], v[206:209], v[84:87], v[20:35]
	v_exp_f32_e32 v175, v175
	v_exp_f32_e32 v176, v176
	v_exp_f32_e32 v177, v177
	v_mfma_f32_16x16x32_bf16 v[244:247], v[84:87], v[218:221], v[244:247]
	s_waitcnt lgkmcnt(0)
	v_mfma_f32_32x32x16_bf16 v[68:83], v[186:189], v[120:123], v[224:239]
	v_cvt_pk_bf16_f32 v170, v170, v171
	v_cvt_pk_bf16_f32 v171, v172, v173
	v_cvt_pk_bf16_f32 v172, v174, v175
	v_cvt_pk_bf16_f32 v173, v176, v177
	v_exp_f32_e32 v92, v92
	v_exp_f32_e32 v93, v93
	v_mfma_f32_32x32x16_bf16 v[36:51], v[202:205], v[170:173], v[36:51]
	v_exp_f32_e32 v94, v94
	v_exp_f32_e32 v95, v95
	v_exp_f32_e32 v96, v96
	v_mfma_f32_32x32x16_bf16 v[52:67], v[206:209], v[170:173], v[52:67]
	v_exp_f32_e32 v97, v97
	v_exp_f32_e32 v98, v98
	v_exp_f32_e32 v99, v99
	v_mfma_f32_16x16x32_bf16 v[248:251], v[170:173], v[218:221], v[248:251]
	v_mfma_f32_32x32x16_bf16 v[68:83], v[190:193], v[108:111], v[68:83]
	v_mfma_f32_32x32x16_bf16 v[154:169], v[194:197], v[116:119], v[224:239]
	v_cvt_pk_bf16_f32 v92, v92, v93
	v_cvt_pk_bf16_f32 v93, v94, v95
	v_cvt_pk_bf16_f32 v94, v96, v97
	v_cvt_pk_bf16_f32 v95, v98, v99
	v_exp_f32_e32 v178, v178
	v_exp_f32_e32 v179, v179
	v_mfma_f32_32x32x16_bf16 v[4:19], v[210:213], v[92:95], v[4:19]
	v_exp_f32_e32 v180, v180
	v_exp_f32_e32 v181, v181
	v_exp_f32_e32 v182, v182
	v_mfma_f32_32x32x16_bf16 v[20:35], v[214:217], v[92:95], v[20:35]
	v_exp_f32_e32 v183, v183
	v_exp_f32_e32 v184, v184
	v_exp_f32_e32 v185, v185
	v_mfma_f32_16x16x32_bf16 v[244:247], v[92:95], v[218:221], v[244:247]
	v_mfma_f32_32x32x16_bf16 v[154:169], v[198:201], v[124:127], v[154:169]
	v_cvt_pk_bf16_f32 v178, v178, v179
	v_cvt_pk_bf16_f32 v179, v180, v181
	v_cvt_pk_bf16_f32 v180, v182, v183
	v_cvt_pk_bf16_f32 v181, v184, v185
	s_nop 1
	v_mfma_f32_16x16x32_bf16 v[248:251], v[178:181], v[218:221], v[248:251]
	v_mfma_f32_32x32x16_bf16 v[36:51], v[210:213], v[178:181], v[36:51]
	v_mfma_f32_32x32x16_bf16 v[52:67], v[214:217], v[178:181], v[52:67]
	ds_read_b128 v[202:205], v240 offset:13824
	ds_read_b128 v[206:209], v240 offset:13856
	ds_read_b128 v[210:213], v240 offset:13888
	ds_read_b128 v[214:217], v240 offset:13920
	ds_read_b64_tr_b16 v[186:187], v241 offset:27648
	ds_read_b64_tr_b16 v[188:189], v241 offset:28800
	ds_read_b64_tr_b16 v[190:191], v241 offset:27712
	ds_read_b64_tr_b16 v[192:193], v241 offset:28864
	ds_read_b64_tr_b16 v[194:195], v241 offset:29952
	ds_read_b64_tr_b16 v[196:197], v241 offset:31104
	ds_read_b64_tr_b16 v[198:199], v241 offset:30016
	ds_read_b64_tr_b16 v[200:201], v241 offset:31168
	v_max3_f32 v84, v244, v245, v246
	v_max3_f32 v84, v84, v247, v248
	v_max3_f32 v84, v84, v249, v250
	v_max_f32_e32 v84, v84, v251
	v_cmp_lt_f32_e32 vcc, 0x49800000, v84
	s_cbranch_vccz .Lat_norescale_a
	v_bfe_u32 v94, v222, 2, 2
	v_lshlrev_b32_e32 v94, 6, v94
	v_bfe_u32 v95, v222, 4, 1
	v_lshl_or_b32 v94, v95, 2, v94
	ds_bpermute_b32 v84, v94, v244
	ds_bpermute_b32 v85, v94, v245
	ds_bpermute_b32 v86, v94, v246
	ds_bpermute_b32 v87, v94, v247
	ds_bpermute_b32 v88, v94, v248
	ds_bpermute_b32 v89, v94, v249
	ds_bpermute_b32 v90, v94, v250
	ds_bpermute_b32 v91, v94, v251
	v_and_b32_e32 v95, 3, v222
	s_waitcnt lgkmcnt(0)
	v_cmp_eq_u32_e32 vcc, 1, v95
	v_cndmask_b32_e32 v92, v84, v85, vcc
	v_cndmask_b32_e32 v93, v88, v89, vcc
	v_cmp_eq_u32_e32 vcc, 2, v95
	v_cndmask_b32_e32 v92, v92, v86, vcc
	v_cndmask_b32_e32 v93, v93, v90, vcc
	v_cmp_eq_u32_e32 vcc, 3, v95
	v_cndmask_b32_e32 v92, v92, v87, vcc
	v_cndmask_b32_e32 v93, v93, v91, vcc
	v_max_f32_e32 v96, v92, v93
	v_log_f32_e32 v96, v96
	s_nop 0
	v_max_f32_e32 v96, 0, v96
	v_add_f32_e32 v243, v243, v96
	v_exp_f32_e64 v98, -v96
	v_xor_b32_e32 v224, 0x80000000, v243
	v_mov_b32_e32 v225, v224
	v_mov_b32_e32 v226, v224
	v_mov_b32_e32 v227, v224
	v_mov_b32_e32 v228, v224
	v_mov_b32_e32 v229, v224
	v_mov_b32_e32 v230, v224
	v_mov_b32_e32 v231, v224
	v_mov_b32_e32 v232, v224
	v_mov_b32_e32 v233, v224
	v_mov_b32_e32 v234, v224
	v_mov_b32_e32 v235, v224
	v_mov_b32_e32 v236, v224
	v_mov_b32_e32 v237, v224
	v_mov_b32_e32 v238, v224
	v_mov_b32_e32 v239, v224
	v_sub_f32_e32 v68, v68, v96
	v_sub_f32_e32 v69, v69, v96
	v_sub_f32_e32 v70, v70, v96
	v_sub_f32_e32 v71, v71, v96
	v_sub_f32_e32 v72, v72, v96
	v_sub_f32_e32 v73, v73, v96
	v_sub_f32_e32 v74, v74, v96
	v_sub_f32_e32 v75, v75, v96
	v_sub_f32_e32 v76, v76, v96
	v_sub_f32_e32 v77, v77, v96
	v_sub_f32_e32 v78, v78, v96
	v_sub_f32_e32 v79, v79, v96
	v_sub_f32_e32 v80, v80, v96
	v_sub_f32_e32 v81, v81, v96
	v_sub_f32_e32 v82, v82, v96
	v_sub_f32_e32 v83, v83, v96
	v_sub_f32_e32 v154, v154, v96
	v_sub_f32_e32 v155, v155, v96
	v_sub_f32_e32 v156, v156, v96
	v_sub_f32_e32 v157, v157, v96
	v_sub_f32_e32 v158, v158, v96
	v_sub_f32_e32 v159, v159, v96
	v_sub_f32_e32 v160, v160, v96
	v_sub_f32_e32 v161, v161, v96
	v_sub_f32_e32 v162, v162, v96
	v_sub_f32_e32 v163, v163, v96
	v_sub_f32_e32 v164, v164, v96
	v_sub_f32_e32 v165, v165, v96
	v_sub_f32_e32 v166, v166, v96
	v_sub_f32_e32 v167, v167, v96
	v_sub_f32_e32 v168, v168, v96
	v_sub_f32_e32 v169, v169, v96
	v_bfe_u32 v170, v222, 4, 2
	v_lshlrev_b32_e32 v170, 4, v170
	v_and_b32_e32 v171, 1, v222
	v_lshl_or_b32 v170, v171, 6, v170
	v_add_u32_e32 v171, 4, v170
	v_add_u32_e32 v172, 8, v170
	v_add_u32_e32 v173, 12, v170
	ds_bpermute_b32 v174, v170, v98
	ds_bpermute_b32 v175, v171, v98
	ds_bpermute_b32 v176, v172, v98
	ds_bpermute_b32 v177, v173, v98
	v_pk_mul_f32 v[4:5], v[4:5], v[98:99] op_sel_hi:[1,0]
	v_pk_mul_f32 v[6:7], v[6:7], v[98:99] op_sel_hi:[1,0]
	v_pk_mul_f32 v[8:9], v[8:9], v[98:99] op_sel_hi:[1,0]
	v_pk_mul_f32 v[10:11], v[10:11], v[98:99] op_sel_hi:[1,0]
	v_pk_mul_f32 v[12:13], v[12:13], v[98:99] op_sel_hi:[1,0]
	v_pk_mul_f32 v[14:15], v[14:15], v[98:99] op_sel_hi:[1,0]
	v_pk_mul_f32 v[16:17], v[16:17], v[98:99] op_sel_hi:[1,0]
	v_pk_mul_f32 v[18:19], v[18:19], v[98:99] op_sel_hi:[1,0]
	v_pk_mul_f32 v[20:21], v[20:21], v[98:99] op_sel_hi:[1,0]
	v_pk_mul_f32 v[22:23], v[22:23], v[98:99] op_sel_hi:[1,0]
	v_pk_mul_f32 v[24:25], v[24:25], v[98:99] op_sel_hi:[1,0]
	v_pk_mul_f32 v[26:27], v[26:27], v[98:99] op_sel_hi:[1,0]
	v_pk_mul_f32 v[28:29], v[28:29], v[98:99] op_sel_hi:[1,0]
	v_pk_mul_f32 v[30:31], v[30:31], v[98:99] op_sel_hi:[1,0]
	v_pk_mul_f32 v[32:33], v[32:33], v[98:99] op_sel_hi:[1,0]
	v_pk_mul_f32 v[34:35], v[34:35], v[98:99] op_sel_hi:[1,0]
	v_pk_mul_f32 v[36:37], v[36:37], v[98:99] op_sel_hi:[1,0]
	v_pk_mul_f32 v[38:39], v[38:39], v[98:99] op_sel_hi:[1,0]
	v_pk_mul_f32 v[40:41], v[40:41], v[98:99] op_sel_hi:[1,0]
	v_pk_mul_f32 v[42:43], v[42:43], v[98:99] op_sel_hi:[1,0]
	v_pk_mul_f32 v[44:45], v[44:45], v[98:99] op_sel_hi:[1,0]
	v_pk_mul_f32 v[46:47], v[46:47], v[98:99] op_sel_hi:[1,0]
	v_pk_mul_f32 v[48:49], v[48:49], v[98:99] op_sel_hi:[1,0]
	v_pk_mul_f32 v[50:51], v[50:51], v[98:99] op_sel_hi:[1,0]
	v_pk_mul_f32 v[52:53], v[52:53], v[98:99] op_sel_hi:[1,0]
	v_pk_mul_f32 v[54:55], v[54:55], v[98:99] op_sel_hi:[1,0]
	v_pk_mul_f32 v[56:57], v[56:57], v[98:99] op_sel_hi:[1,0]
	v_pk_mul_f32 v[58:59], v[58:59], v[98:99] op_sel_hi:[1,0]
	v_pk_mul_f32 v[60:61], v[60:61], v[98:99] op_sel_hi:[1,0]
	v_pk_mul_f32 v[62:63], v[62:63], v[98:99] op_sel_hi:[1,0]
	v_pk_mul_f32 v[64:65], v[64:65], v[98:99] op_sel_hi:[1,0]
	v_pk_mul_f32 v[66:67], v[66:67], v[98:99] op_sel_hi:[1,0]
	s_waitcnt lgkmcnt(0)
	v_mul_f32_e32 v244, v244, v174
	v_mul_f32_e32 v248, v248, v174
	v_mul_f32_e32 v245, v245, v175
	v_mul_f32_e32 v249, v249, v175
	v_mul_f32_e32 v246, v246, v176
	v_mul_f32_e32 v250, v250, v176
	v_mul_f32_e32 v247, v247, v177
	v_mul_f32_e32 v251, v251, v177
.Lat_norescale_a:
	v_exp_f32_e32 v68, v68
	v_exp_f32_e32 v69, v69
	s_waitcnt lgkmcnt(8)
	v_mfma_f32_32x32x16_bf16 v[84:99], v[202:205], v[120:123], v[224:239]
	ds_read_b64_tr_b16 v[202:203], v242 offset:32256
	ds_read_b64_tr_b16 v[204:205], v242 offset:33408
	v_exp_f32_e32 v70, v70
	v_exp_f32_e32 v71, v71
	v_exp_f32_e32 v72, v72
	v_mfma_f32_32x32x16_bf16 v[84:99], v[206:209], v[108:111], v[84:99]
	ds_read_b64_tr_b16 v[206:207], v242 offset:32320
	ds_read_b64_tr_b16 v[208:209], v242 offset:33472
	v_exp_f32_e32 v73, v73
	v_exp_f32_e32 v74, v74
	v_exp_f32_e32 v75, v75
	v_mfma_f32_32x32x16_bf16 v[170:185], v[210:213], v[116:119], v[224:239]
	ds_read_b64_tr_b16 v[210:211], v242 offset:34560
	ds_read_b64_tr_b16 v[212:213], v242 offset:35712
	v_cvt_pk_bf16_f32 v68, v68, v69
	v_cvt_pk_bf16_f32 v69, v70, v71
	v_cvt_pk_bf16_f32 v70, v72, v73
	v_cvt_pk_bf16_f32 v71, v74, v75
	v_exp_f32_e32 v154, v154
	v_exp_f32_e32 v155, v155
	s_waitcnt lgkmcnt(10)
	v_mfma_f32_32x32x16_bf16 v[4:19], v[186:189], v[68:71], v[4:19]
	v_exp_f32_e32 v156, v156
	v_exp_f32_e32 v157, v157
	v_exp_f32_e32 v158, v158
	v_mfma_f32_32x32x16_bf16 v[20:35], v[190:193], v[68:71], v[20:35]
	v_exp_f32_e32 v159, v159
	v_exp_f32_e32 v160, v160
	v_exp_f32_e32 v161, v161
	v_mfma_f32_16x16x32_bf16 v[244:247], v[68:71], v[218:221], v[244:247]
	v_mfma_f32_32x32x16_bf16 v[170:185], v[214:217], v[124:127], v[170:185]
	ds_read_b64_tr_b16 v[214:215], v242 offset:34624
	ds_read_b64_tr_b16 v[216:217], v242 offset:35776
	v_cvt_pk_bf16_f32 v154, v154, v155
	v_cvt_pk_bf16_f32 v155, v156, v157
	v_cvt_pk_bf16_f32 v156, v158, v159
	v_cvt_pk_bf16_f32 v157, v160, v161
	v_exp_f32_e32 v76, v76
	v_exp_f32_e32 v77, v77
	v_mfma_f32_32x32x16_bf16 v[36:51], v[186:189], v[154:157], v[36:51]
	v_exp_f32_e32 v78, v78
	v_exp_f32_e32 v79, v79
	v_exp_f32_e32 v80, v80
	v_mfma_f32_32x32x16_bf16 v[52:67], v[190:193], v[154:157], v[52:67]
	v_exp_f32_e32 v81, v81
	v_exp_f32_e32 v82, v82
	v_exp_f32_e32 v83, v83
	v_mfma_f32_16x16x32_bf16 v[248:251], v[154:157], v[218:221], v[248:251]
	v_cvt_pk_bf16_f32 v76, v76, v77
	v_cvt_pk_bf16_f32 v77, v78, v79
	v_cvt_pk_bf16_f32 v78, v80, v81
	v_cvt_pk_bf16_f32 v79, v82, v83
	v_exp_f32_e32 v162, v162
	v_exp_f32_e32 v163, v163
	s_waitcnt lgkmcnt(8)
	v_mfma_f32_32x32x16_bf16 v[4:19], v[194:197], v[76:79], v[4:19]
	v_exp_f32_e32 v164, v164
	v_exp_f32_e32 v165, v165
	v_exp_f32_e32 v166, v166
	v_mfma_f32_32x32x16_bf16 v[20:35], v[198:201], v[76:79], v[20:35]
	v_exp_f32_e32 v167, v167
	v_exp_f32_e32 v168, v168
	v_exp_f32_e32 v169, v169
	v_mfma_f32_16x16x32_bf16 v[244:247], v[76:79], v[218:221], v[244:247]
	v_cvt_pk_bf16_f32 v162, v162, v163
	v_cvt_pk_bf16_f32 v163, v164, v165
	v_cvt_pk_bf16_f32 v164, v166, v167
	v_cvt_pk_bf16_f32 v165, v168, v169
	s_waitcnt lgkmcnt(0)
	s_barrier
	s_and_b64 vcc, exec, s[12:13]
	s_cbranch_vccnz .Lat_norefill_b
	s_add_i32 s4, s39, 4
	s_cmp_ge_u32 s4, s38
	s_cbranch_scc1 .Lat_refill_last_b
	s_waitcnt vmcnt(4)
	ds_write_b128 v254, v[132:135] offset:9216
	ds_write_b128 v254, v[136:139] offset:13824
	ds_write_b128 v254, v[140:143] offset:27648
	ds_write_b128 v254, v[144:147] offset:32256
	s_add_u32 s4, s0, 0x73c5000
	s_addc_u32 s5, s1, 0
	s_add_u32 s6, s0, 0x73fd000
	s_addc_u32 s7, s1, 0
	v_lshl_add_u64 v[72:73], v[150:151], 0, s[4:5]
	v_lshl_add_u64 v[74:75], v[150:151], 0, s[6:7]
	global_load_dwordx4 v[132:135], v[72:73], off offset:1536
	global_load_dwordx4 v[140:143], v[72:73], off offset:2048
	global_load_dwordx4 v[136:139], v[74:75], off offset:1536
	global_load_dwordx4 v[144:147], v[74:75], off offset:2048
	s_branch .Lat_norefill_b
.Lat_refill_last_b:
	s_waitcnt vmcnt(0)
	ds_write_b128 v254, v[132:135] offset:9216
	ds_write_b128 v254, v[136:139] offset:13824
	ds_write_b128 v254, v[140:143] offset:27648
	ds_write_b128 v254, v[144:147] offset:32256
.Lat_norefill_b:
	v_exp_f32_e32 v84, v84
	v_exp_f32_e32 v85, v85
	v_mfma_f32_32x32x16_bf16 v[36:51], v[194:197], v[162:165], v[36:51]
	v_exp_f32_e32 v86, v86
	v_exp_f32_e32 v87, v87
	v_exp_f32_e32 v88, v88
	v_mfma_f32_32x32x16_bf16 v[52:67], v[198:201], v[162:165], v[52:67]
	ds_read_b128 v[186:189], v240
	ds_read_b128 v[190:193], v240 offset:32
	ds_read_b128 v[194:197], v240 offset:64
	ds_read_b128 v[198:201], v240 offset:96
	v_exp_f32_e32 v89, v89
	v_exp_f32_e32 v90, v90
	v_exp_f32_e32 v91, v91
	v_mfma_f32_16x16x32_bf16 v[248:251], v[162:165], v[218:221], v[248:251]
	v_cvt_pk_bf16_f32 v84, v84, v85
	v_cvt_pk_bf16_f32 v85, v86, v87
	v_cvt_pk_bf16_f32 v86, v88, v89
	v_cvt_pk_bf16_f32 v87, v90, v91
	v_exp_f32_e32 v170, v170
	v_exp_f32_e32 v171, v171
	v_mfma_f32_32x32x16_bf16 v[4:19], v[202:205], v[84:87], v[4:19]
	v_exp_f32_e32 v172, v172
	v_exp_f32_e32 v173, v173
	v_exp_f32_e32 v174, v174
	v_mfma_f32_32x32x16_bf16 v[20:35], v[206:209], v[84:87], v[20:35]
	v_exp_f32_e32 v175, v175
	v_exp_f32_e32 v176, v176
	v_exp_f32_e32 v177, v177
	v_mfma_f32_16x16x32_bf16 v[244:247], v[84:87], v[218:221], v[244:247]
	s_waitcnt lgkmcnt(0)
	v_mfma_f32_32x32x16_bf16 v[68:83], v[186:189], v[120:123], v[224:239]
	v_cvt_pk_bf16_f32 v170, v170, v171
	v_cvt_pk_bf16_f32 v171, v172, v173
	v_cvt_pk_bf16_f32 v172, v174, v175
	v_cvt_pk_bf16_f32 v173, v176, v177
	v_exp_f32_e32 v92, v92
	v_exp_f32_e32 v93, v93
	v_mfma_f32_32x32x16_bf16 v[36:51], v[202:205], v[170:173], v[36:51]
	v_exp_f32_e32 v94, v94
	v_exp_f32_e32 v95, v95
	v_exp_f32_e32 v96, v96
	v_mfma_f32_32x32x16_bf16 v[52:67], v[206:209], v[170:173], v[52:67]
	v_exp_f32_e32 v97, v97
	v_exp_f32_e32 v98, v98
	v_exp_f32_e32 v99, v99
	v_mfma_f32_16x16x32_bf16 v[248:251], v[170:173], v[218:221], v[248:251]
	v_mfma_f32_32x32x16_bf16 v[68:83], v[190:193], v[108:111], v[68:83]
	v_mfma_f32_32x32x16_bf16 v[154:169], v[194:197], v[116:119], v[224:239]
	v_cvt_pk_bf16_f32 v92, v92, v93
	v_cvt_pk_bf16_f32 v93, v94, v95
	v_cvt_pk_bf16_f32 v94, v96, v97
	v_cvt_pk_bf16_f32 v95, v98, v99
	v_exp_f32_e32 v178, v178
	v_exp_f32_e32 v179, v179
	v_mfma_f32_32x32x16_bf16 v[4:19], v[210:213], v[92:95], v[4:19]
	v_exp_f32_e32 v180, v180
	v_exp_f32_e32 v181, v181
	v_exp_f32_e32 v182, v182
	v_mfma_f32_32x32x16_bf16 v[20:35], v[214:217], v[92:95], v[20:35]
	v_exp_f32_e32 v183, v183
	v_exp_f32_e32 v184, v184
	v_exp_f32_e32 v185, v185
	v_mfma_f32_16x16x32_bf16 v[244:247], v[92:95], v[218:221], v[244:247]
	v_mfma_f32_32x32x16_bf16 v[154:169], v[198:201], v[124:127], v[154:169]
	v_cvt_pk_bf16_f32 v178, v178, v179
	v_cvt_pk_bf16_f32 v179, v180, v181
	v_cvt_pk_bf16_f32 v180, v182, v183
	v_cvt_pk_bf16_f32 v181, v184, v185
	s_nop 1
	v_mfma_f32_16x16x32_bf16 v[248:251], v[178:181], v[218:221], v[248:251]
	v_mfma_f32_32x32x16_bf16 v[36:51], v[210:213], v[178:181], v[36:51]
	v_mfma_f32_32x32x16_bf16 v[52:67], v[214:217], v[178:181], v[52:67]
	ds_read_b128 v[202:205], v240 offset:4608
	ds_read_b128 v[206:209], v240 offset:4640
	ds_read_b128 v[210:213], v240 offset:4672
	ds_read_b128 v[214:217], v240 offset:4704
	ds_read_b64_tr_b16 v[186:187], v241 offset:18432
	ds_read_b64_tr_b16 v[188:189], v241 offset:19584
	ds_read_b64_tr_b16 v[190:191], v241 offset:18496
	ds_read_b64_tr_b16 v[192:193], v241 offset:19648
	ds_read_b64_tr_b16 v[194:195], v241 offset:20736
	ds_read_b64_tr_b16 v[196:197], v241 offset:21888
	ds_read_b64_tr_b16 v[198:199], v241 offset:20800
	ds_read_b64_tr_b16 v[200:201], v241 offset:21952
	v_max3_f32 v84, v244, v245, v246
	v_max3_f32 v84, v84, v247, v248
	v_max3_f32 v84, v84, v249, v250
	v_max_f32_e32 v84, v84, v251
	v_cmp_lt_f32_e32 vcc, 0x49800000, v84
	s_cbranch_vccz .Lat_norescale_b
	v_bfe_u32 v94, v222, 2, 2
	v_lshlrev_b32_e32 v94, 6, v94
	v_bfe_u32 v95, v222, 4, 1
	v_lshl_or_b32 v94, v95, 2, v94
	ds_bpermute_b32 v84, v94, v244
	ds_bpermute_b32 v85, v94, v245
	ds_bpermute_b32 v86, v94, v246
	ds_bpermute_b32 v87, v94, v247
	ds_bpermute_b32 v88, v94, v248
	ds_bpermute_b32 v89, v94, v249
	ds_bpermute_b32 v90, v94, v250
	ds_bpermute_b32 v91, v94, v251
	v_and_b32_e32 v95, 3, v222
	s_waitcnt lgkmcnt(0)
	v_cmp_eq_u32_e32 vcc, 1, v95
	v_cndmask_b32_e32 v92, v84, v85, vcc
	v_cndmask_b32_e32 v93, v88, v89, vcc
	v_cmp_eq_u32_e32 vcc, 2, v95
	v_cndmask_b32_e32 v92, v92, v86, vcc
	v_cndmask_b32_e32 v93, v93, v90, vcc
	v_cmp_eq_u32_e32 vcc, 3, v95
	v_cndmask_b32_e32 v92, v92, v87, vcc
	v_cndmask_b32_e32 v93, v93, v91, vcc
	v_max_f32_e32 v96, v92, v93
	v_log_f32_e32 v96, v96
	s_nop 0
	v_max_f32_e32 v96, 0, v96
	v_add_f32_e32 v243, v243, v96
	v_exp_f32_e64 v98, -v96
	v_xor_b32_e32 v224, 0x80000000, v243
	v_mov_b32_e32 v225, v224
	v_mov_b32_e32 v226, v224
	v_mov_b32_e32 v227, v224
	v_mov_b32_e32 v228, v224
	v_mov_b32_e32 v229, v224
	v_mov_b32_e32 v230, v224
	v_mov_b32_e32 v231, v224
	v_mov_b32_e32 v232, v224
	v_mov_b32_e32 v233, v224
	v_mov_b32_e32 v234, v224
	v_mov_b32_e32 v235, v224
	v_mov_b32_e32 v236, v224
	v_mov_b32_e32 v237, v224
	v_mov_b32_e32 v238, v224
	v_mov_b32_e32 v239, v224
	v_sub_f32_e32 v68, v68, v96
	v_sub_f32_e32 v69, v69, v96
	v_sub_f32_e32 v70, v70, v96
	v_sub_f32_e32 v71, v71, v96
	v_sub_f32_e32 v72, v72, v96
	v_sub_f32_e32 v73, v73, v96
	v_sub_f32_e32 v74, v74, v96
	v_sub_f32_e32 v75, v75, v96
	v_sub_f32_e32 v76, v76, v96
	v_sub_f32_e32 v77, v77, v96
	v_sub_f32_e32 v78, v78, v96
	v_sub_f32_e32 v79, v79, v96
	v_sub_f32_e32 v80, v80, v96
	v_sub_f32_e32 v81, v81, v96
	v_sub_f32_e32 v82, v82, v96
	v_sub_f32_e32 v83, v83, v96
	v_sub_f32_e32 v154, v154, v96
	v_sub_f32_e32 v155, v155, v96
	v_sub_f32_e32 v156, v156, v96
	v_sub_f32_e32 v157, v157, v96
	v_sub_f32_e32 v158, v158, v96
	v_sub_f32_e32 v159, v159, v96
	v_sub_f32_e32 v160, v160, v96
	v_sub_f32_e32 v161, v161, v96
	v_sub_f32_e32 v162, v162, v96
	v_sub_f32_e32 v163, v163, v96
	v_sub_f32_e32 v164, v164, v96
	v_sub_f32_e32 v165, v165, v96
	v_sub_f32_e32 v166, v166, v96
	v_sub_f32_e32 v167, v167, v96
	v_sub_f32_e32 v168, v168, v96
	v_sub_f32_e32 v169, v169, v96
	v_bfe_u32 v170, v222, 4, 2
	v_lshlrev_b32_e32 v170, 4, v170
	v_and_b32_e32 v171, 1, v222
	v_lshl_or_b32 v170, v171, 6, v170
	v_add_u32_e32 v171, 4, v170
	v_add_u32_e32 v172, 8, v170
	v_add_u32_e32 v173, 12, v170
	ds_bpermute_b32 v174, v170, v98
	ds_bpermute_b32 v175, v171, v98
	ds_bpermute_b32 v176, v172, v98
	ds_bpermute_b32 v177, v173, v98
	v_pk_mul_f32 v[4:5], v[4:5], v[98:99] op_sel_hi:[1,0]
	v_pk_mul_f32 v[6:7], v[6:7], v[98:99] op_sel_hi:[1,0]
	v_pk_mul_f32 v[8:9], v[8:9], v[98:99] op_sel_hi:[1,0]
	v_pk_mul_f32 v[10:11], v[10:11], v[98:99] op_sel_hi:[1,0]
	v_pk_mul_f32 v[12:13], v[12:13], v[98:99] op_sel_hi:[1,0]
	v_pk_mul_f32 v[14:15], v[14:15], v[98:99] op_sel_hi:[1,0]
	v_pk_mul_f32 v[16:17], v[16:17], v[98:99] op_sel_hi:[1,0]
	v_pk_mul_f32 v[18:19], v[18:19], v[98:99] op_sel_hi:[1,0]
	v_pk_mul_f32 v[20:21], v[20:21], v[98:99] op_sel_hi:[1,0]
	v_pk_mul_f32 v[22:23], v[22:23], v[98:99] op_sel_hi:[1,0]
	v_pk_mul_f32 v[24:25], v[24:25], v[98:99] op_sel_hi:[1,0]
	v_pk_mul_f32 v[26:27], v[26:27], v[98:99] op_sel_hi:[1,0]
	v_pk_mul_f32 v[28:29], v[28:29], v[98:99] op_sel_hi:[1,0]
	v_pk_mul_f32 v[30:31], v[30:31], v[98:99] op_sel_hi:[1,0]
	v_pk_mul_f32 v[32:33], v[32:33], v[98:99] op_sel_hi:[1,0]
	v_pk_mul_f32 v[34:35], v[34:35], v[98:99] op_sel_hi:[1,0]
	v_pk_mul_f32 v[36:37], v[36:37], v[98:99] op_sel_hi:[1,0]
	v_pk_mul_f32 v[38:39], v[38:39], v[98:99] op_sel_hi:[1,0]
	v_pk_mul_f32 v[40:41], v[40:41], v[98:99] op_sel_hi:[1,0]
	v_pk_mul_f32 v[42:43], v[42:43], v[98:99] op_sel_hi:[1,0]
	v_pk_mul_f32 v[44:45], v[44:45], v[98:99] op_sel_hi:[1,0]
	v_pk_mul_f32 v[46:47], v[46:47], v[98:99] op_sel_hi:[1,0]
	v_pk_mul_f32 v[48:49], v[48:49], v[98:99] op_sel_hi:[1,0]
	v_pk_mul_f32 v[50:51], v[50:51], v[98:99] op_sel_hi:[1,0]
	v_pk_mul_f32 v[52:53], v[52:53], v[98:99] op_sel_hi:[1,0]
	v_pk_mul_f32 v[54:55], v[54:55], v[98:99] op_sel_hi:[1,0]
	v_pk_mul_f32 v[56:57], v[56:57], v[98:99] op_sel_hi:[1,0]
	v_pk_mul_f32 v[58:59], v[58:59], v[98:99] op_sel_hi:[1,0]
	v_pk_mul_f32 v[60:61], v[60:61], v[98:99] op_sel_hi:[1,0]
	v_pk_mul_f32 v[62:63], v[62:63], v[98:99] op_sel_hi:[1,0]
	v_pk_mul_f32 v[64:65], v[64:65], v[98:99] op_sel_hi:[1,0]
	v_pk_mul_f32 v[66:67], v[66:67], v[98:99] op_sel_hi:[1,0]
	s_waitcnt lgkmcnt(0)
	v_mul_f32_e32 v244, v244, v174
	v_mul_f32_e32 v248, v248, v174
	v_mul_f32_e32 v245, v245, v175
	v_mul_f32_e32 v249, v249, v175
	v_mul_f32_e32 v246, v246, v176
	v_mul_f32_e32 v250, v250, v176
	v_mul_f32_e32 v247, v247, v177
	v_mul_f32_e32 v251, v251, v177
.Lat_norescale_b:
	s_add_u32 s0, s0, 0xe0000
	s_addc_u32 s1, s1, 0
	s_andn2_b64 vcc, exec, s[12:13]
	s_cbranch_vccnz .Lat_more
	s_waitcnt lgkmcnt(0)
	s_barrier
	v_bfe_u32 v94, v222, 2, 2
	v_lshlrev_b32_e32 v94, 6, v94
	v_bfe_u32 v95, v222, 4, 1
	v_lshl_or_b32 v94, v95, 2, v94
	ds_bpermute_b32 v84, v94, v244
	ds_bpermute_b32 v85, v94, v245
	ds_bpermute_b32 v86, v94, v246
	ds_bpermute_b32 v87, v94, v247
	ds_bpermute_b32 v88, v94, v248
	ds_bpermute_b32 v89, v94, v249
	ds_bpermute_b32 v90, v94, v250
	ds_bpermute_b32 v91, v94, v251
	v_and_b32_e32 v95, 3, v222
	s_waitcnt lgkmcnt(0)
	v_cmp_eq_u32_e32 vcc, 1, v95
	v_cndmask_b32_e32 v92, v84, v85, vcc
	v_cndmask_b32_e32 v93, v88, v89, vcc
	v_cmp_eq_u32_e32 vcc, 2, v95
	v_cndmask_b32_e32 v92, v92, v86, vcc
	v_cndmask_b32_e32 v93, v93, v90, vcc
	v_cmp_eq_u32_e32 vcc, 3, v95
	v_cndmask_b32_e32 v92, v92, v87, vcc
	v_cndmask_b32_e32 v93, v93, v91, vcc
	v_mul_f32_e32 v152, 0.5, v92
	v_mul_f32_e32 v153, 0.5, v93
	v_mov_b32_e32 v219, v223
	v_mov_b32_e32 v218, 0x3f317218
	v_mov_b32_e32 v223, 0x358637bd
	v_mov_b32_e32 v224, 0x1000
	v_mov_b32_e32 v225, 0x2000
	v_mov_b32_e32 v226, 1
	v_mov_b32_e32 v227, 0x3727c5ac
	v_mov_b32_e32 v228, 0x3ecc95a3
	v_bfrev_b32_e32 v229, 0.5
	v_mov_b32_e32 v230, 0x41b17218
	v_mov_b32_e32 v231, 0x3e8293ee
	v_mov_b32_e32 v232, 0xfffff000
	v_mov_b32_e32 v233, 0x1c00
	v_mov_b32_e32 v234, 0x7f800000
	v_mov_b32_e32 v235, 0x7fc00000
	v_mov_b32_e32 v236, 0xff800000
	v_mov_b32_e32 v237, 0x1dc0000
	v_mov_b32_e32 v238, 0x1100
	s_branch .LBB0_541
